# P0 w_in/w_up transposes touch the next tile of the same virtual block (L2 prefetch) and wait vmcnt(4) for their own loads
# baseline (speedup 1.0000x reference)
.LBB0_48:
	s_andn2_saveexec_b64 s[48:49], s[48:49]
	s_cbranch_execz .LBB0_52
	v_mov_b32_e32 v2, s82
	v_mov_b32_e32 v4, s63
	ds_read_b64 v[2:3], v2
	ds_read_b64 v[4:5], v4
	v_lshlrev_b32_e32 v8, 6, v1
	v_and_or_b32 v8, v8, s59, v77
	v_lshl_add_u32 v61, v1, 2, v96
	v_mul_u32_u24_e32 v8, 0x1600, v8
	v_and_b32_e32 v61, 0x3ffc0, v61
	v_lshlrev_b32_e32 v68, 2, v8
	v_mov_b32_e32 v69, v9
	s_waitcnt lgkmcnt(0)
	v_add_co_u32_e32 v2, vcc, v2, v68
	v_addc_co_u32_e32 v3, vcc, v3, v69, vcc
	v_lshlrev_b32_e32 v68, 2, v61
	v_add_co_u32_e32 v2, vcc, v2, v68
	v_addc_co_u32_e32 v3, vcc, v3, v69, vcc
	v_lshlrev_b32_e32 v68, 2, v6
	v_add_co_u32_e32 v2, vcc, v2, v68
	v_addc_co_u32_e32 v3, vcc, v3, v69, vcc
	v_add_co_u32_e32 v68, vcc, s81, v2
	v_mov_b32_e32 v71, v9
	s_nop 0
	v_addc_co_u32_e32 v69, vcc, 0, v3, vcc
	global_load_dwordx4 v[98:101], v[2:3], off
	global_load_dwordx4 v[102:105], v[68:69], off
	v_add_co_u32_e32 v68, vcc, s83, v2
	v_mov_b32_e32 v73, v9
	s_nop 0
	v_addc_co_u32_e32 v69, vcc, 0, v3, vcc
	global_load_dwordx4 v[106:109], v[68:69], off
	v_add_co_u32_e32 v2, vcc, s84, v2
	v_lshl_add_u64 v[114:115], v[4:5], 0, v[14:15]
	s_nop 0
	v_addc_co_u32_e32 v3, vcc, 0, v3, vcc
	global_load_dwordx4 v[110:113], v[2:3], off
	v_mov_b32_e32 v245, 0x2000
	v_cmp_gt_u32_e32 vcc, 0xc80, v1
	s_nop 1
	v_cndmask_b32_e32 v244, v9, v245, vcc
	v_add_co_u32_e32 v240, vcc, v2, v244
	v_addc_co_u32_e32 v241, vcc, 0, v3, vcc
	global_load_dword v251, v[240:241], off
	v_subrev_co_u32_e32 v240, vcc, s81, v240
	v_subbrev_co_u32_e32 v241, vcc, 0, v241, vcc
	global_load_dword v251, v[240:241], off
	v_subrev_co_u32_e32 v240, vcc, s81, v240
	v_subbrev_co_u32_e32 v241, vcc, 0, v241, vcc
	global_load_dword v251, v[240:241], off
	v_subrev_co_u32_e32 v240, vcc, s81, v240
	v_subbrev_co_u32_e32 v241, vcc, 0, v241, vcc
	global_load_dword v251, v[240:241], off
	v_and_b32_e32 v2, 0x3ffc0, v93
	v_or_b32_e32 v3, v90, v2
	v_or_b32_e32 v68, v91, v2
	v_or_b32_e32 v70, v92, v2
	v_or_b32_e32 v2, v75, v2
	v_mov_b32_e32 v69, v9
	v_lshl_or_b32 v8, v3, 11, v23
	v_lshl_or_b32 v68, v68, 11, v23
	v_lshl_or_b32 v70, v70, 11, v23
	v_lshl_or_b32 v72, v2, 11, v23
	s_mov_b64 s[50:51], 0
	v_lshl_add_u64 v[2:3], v[114:115], 0, v[8:9]
	v_lshl_add_u64 v[4:5], v[114:115], 0, v[68:69]
	v_lshl_add_u64 v[68:69], v[114:115], 0, v[70:71]
	v_lshl_add_u64 v[70:71], v[114:115], 0, v[72:73]
	v_mov_b32_e32 v8, v85
	v_add_u32_e32 v61, 0x1040, v78
	v_add_u32_e32 v65, 0x1048, v78
	v_add_u32_e32 v66, 0x2080, v78
	v_add_u32_e32 v116, 0x2088, v78
	v_add_u32_e32 v117, 0x30c0, v78
	v_add_u32_e32 v118, 0x30c8, v78
	s_waitcnt vmcnt(4) lgkmcnt(0)
	ds_write2_b32 v78, v98, v99 offset1:1
	ds_write2_b32 v78, v100, v101 offset0:2 offset1:3
	ds_write2_b32 v61, v102, v103 offset1:1
	ds_write2_b32 v65, v104, v105 offset1:1
	ds_write2_b32 v66, v106, v107 offset1:1
	ds_write2_b32 v116, v108, v109 offset1:1
	ds_write2_b32 v117, v110, v111 offset1:1
	ds_write2_b32 v118, v112, v113 offset1:1
	s_waitcnt lgkmcnt(0)
	s_barrier

.LBB0_68:
	v_mov_b32_e32 v2, s89
	v_mov_b32_e32 v4, s63
	ds_read_b64 v[2:3], v2
	ds_read_b64 v[72:73], v4
	v_ashrrev_i32_e32 v4, 31, v1
	v_lshrrev_b32_e32 v4, 28, v4
	v_add_u32_e32 v4, v1, v4
	v_and_b32_e32 v5, 0x3fffff0, v4
	v_sub_u32_e32 v5, v1, v5
	v_lshlrev_b32_e32 v110, 6, v5
	v_or_b32_e32 v5, v110, v77
	v_lshlrev_b32_e32 v4, 2, v4
	v_mul_lo_u32 v68, v5, s90
	v_and_b32_e32 v4, 0xffffffc0, v4
	v_ashrrev_i32_e32 v69, 31, v68
	s_waitcnt lgkmcnt(0)
	v_lshl_add_u64 v[2:3], v[68:69], 2, v[2:3]
	v_ashrrev_i32_e32 v5, 31, v4
	v_lshl_add_u64 v[2:3], v[4:5], 2, v[2:3]
	v_lshlrev_b32_e32 v8, 2, v6
	v_add_co_u32_e32 v2, vcc, v2, v8
	v_addc_co_u32_e32 v3, vcc, v3, v9, vcc
	v_add_co_u32_e32 v98, vcc, s91, v2
	v_ashrrev_i32_e32 v111, 31, v110
	s_nop 0
	v_addc_co_u32_e32 v99, vcc, 0, v3, vcc
	global_load_dwordx4 v[68:71], v[2:3], off
	s_nop 0
	global_load_dwordx4 v[98:101], v[98:99], off
	v_add_co_u32_e32 v102, vcc, s92, v2
	v_add_u32_e32 v5, 0x1040, v78
	s_nop 0
	v_addc_co_u32_e32 v103, vcc, 0, v3, vcc
	global_load_dwordx4 v[102:105], v[102:103], off
	v_add_co_u32_e32 v2, vcc, s93, v2
	v_mov_b32_e32 v23, v9
	s_nop 0
	v_addc_co_u32_e32 v3, vcc, 0, v3, vcc
	global_load_dwordx4 v[106:109], v[2:3], off
	v_mov_b32_e32 v245, 0x2000
	v_cmp_gt_u32_e32 vcc, 0x480, v1
	s_nop 1
	v_cndmask_b32_e32 v244, v9, v245, vcc
	v_add_co_u32_e32 v240, vcc, v2, v244
	v_addc_co_u32_e32 v241, vcc, 0, v3, vcc
	global_load_dword v251, v[240:241], off
	v_subrev_co_u32_e32 v240, vcc, s91, v240
	v_subbrev_co_u32_e32 v241, vcc, 0, v241, vcc
	global_load_dword v251, v[240:241], off
	v_subrev_co_u32_e32 v240, vcc, s91, v240
	v_subbrev_co_u32_e32 v241, vcc, 0, v241, vcc
	global_load_dword v251, v[240:241], off
	v_subrev_co_u32_e32 v240, vcc, s91, v240
	v_subbrev_co_u32_e32 v241, vcc, 0, v241, vcc
	global_load_dword v251, v[240:241], off
	v_lshl_add_u64 v[2:3], v[110:111], 1, v[72:73]
	s_mov_b32 s34, 0
	v_add_u32_e32 v8, 0x1048, v78
	v_add_u32_e32 v61, 0x2080, v78
	v_add_u32_e32 v65, 0x2088, v78
	v_add_u32_e32 v66, 0x30c0, v78
	v_add_u32_e32 v112, 0x30c8, v78
	v_or_b32_e32 v4, v75, v4
	v_lshl_add_u64 v[2:3], v[2:3], 0, v[22:23]
	s_waitcnt vmcnt(4) lgkmcnt(0)
	ds_write2_b32 v78, v68, v69 offset1:1
	ds_write2_b32 v78, v70, v71 offset0:2 offset1:3
	ds_write2_b32 v5, v98, v99 offset1:1
	ds_write2_b32 v8, v100, v101 offset1:1
	ds_write2_b32 v61, v102, v103 offset1:1
	ds_write2_b32 v65, v104, v105 offset1:1
	ds_write2_b32 v66, v106, v107 offset1:1
	ds_write2_b32 v112, v108, v109 offset1:1
	v_mov_b32_e32 v5, v85
	s_waitcnt lgkmcnt(0)
	s_barrier
